# phase-0 stores write-through (sc1): nothing dirty left for the per-XCD L2 write-back inside the first grid barrier
# speedup vs baseline: 1.0369x; 1.0007x over previous
; #define LAS __attribute__((address_space(3)))
; __device__ __forceinline__ unsigned pk2(float lo, float hi) { return pg8::cvt_pk_bf16(lo, hi); }
; template <int MAP>
; __device__ __forceinline__ void transpose_item(const float* W, int K, int N, bf16_t* WT, const float* gk, LAS float* scr, int item, int nblk, int lane) {
;     ...
;     for (int i = 0; i < 32; ++i) scr[(2 * i + (lane >> 5)) * 33 + (lane & 31)] = tv[i];
;     asm volatile("s_waitcnt lgkmcnt(0)" ::: "memory");
;     const int c = lane & 7;
; #pragma unroll
;     for (int j = 0; j < 4; ++j) { const int n = (lane >> 3) + 8 * j; const LAS float* s = scr + (8 * c) * 33 + n;
;         u32x4 o; o.x = pk2(s[0 * 33], s[1 * 33]); o.y = pk2(s[2 * 33], s[3 * 33]); o.z = pk2(s[4 * 33], s[5 * 33]); o.w = pk2(s[6 * 33], s[7 * 33]);
;         *(u32x4*)(WT + (size_t)(n0 + n) * K + k0 + 8 * c) = o; }
;     asm volatile("s_waitcnt lgkmcnt(0)" ::: "memory");
; __device__ __forceinline__ void phase0(const Args& a, LAS unsigned char* lds) {
;     ...
;         if (r < I_IN) { transpose_item<1>(a.in[2], 1024, 2328, (bf16_t*)(ws + WS_WIN), a.in[1], scr, r, 80, lane); continue; } r -= I_IN;
.LBB0_18:
	s_waitcnt vmcnt(0)
	ds_write2_b32 v49, v10, v11 offset1:66
	ds_write2_b32 v49, v12, v13 offset0:132 offset1:198
	ds_write2_b32 v58, v14, v15 offset0:8 offset1:74
	ds_write2_b32 v58, v16, v17 offset0:140 offset1:206
	ds_write2_b32 v59, v18, v19 offset0:16 offset1:82
	ds_write2_b32 v59, v20, v21 offset0:148 offset1:214
	ds_write2_b32 v60, v22, v23 offset0:24 offset1:90
	ds_write2_b32 v60, v24, v25 offset0:156 offset1:222
	ds_write2_b32 v61, v26, v27 offset0:32 offset1:98
	ds_write2_b32 v61, v30, v31 offset0:164 offset1:230
	ds_write2_b32 v62, v34, v35 offset0:40 offset1:106
	ds_write2_b32 v62, v36, v37 offset0:172 offset1:238
	ds_write2_b32 v63, v38, v39 offset0:48 offset1:114
	ds_write2_b32 v63, v40, v41 offset0:180 offset1:246
	ds_write2_b32 v64, v42, v43 offset0:56 offset1:122
	ds_write2_b32 v64, v44, v45 offset0:188 offset1:254
	s_waitcnt lgkmcnt(0)
	ds_read2_b32 v[10:11], v51 offset1:33
	s_waitcnt lgkmcnt(0)
	v_cvt_pk_bf16_f32 v10, v10, v11
	ds_read2_b32 v[12:13], v51 offset0:66 offset1:99
	s_waitcnt lgkmcnt(0)
	v_cvt_pk_bf16_f32 v11, v12, v13
	ds_read2_b32 v[12:13], v51 offset0:132 offset1:165
	s_waitcnt lgkmcnt(0)
	v_cvt_pk_bf16_f32 v12, v12, v13
	ds_read2_b32 v[14:15], v51 offset0:198 offset1:231
	s_waitcnt lgkmcnt(0)
	v_cvt_pk_bf16_f32 v13, v14, v15
	v_add3_u32 v14, v50, v55, v66
	v_ashrrev_i32_e32 v9, 31, v8
	v_ashrrev_i32_e32 v15, 31, v14
	v_lshl_add_u64 v[16:17], v[8:9], 1, v[6:7]
	v_lshlrev_b64 v[18:19], 11, v[14:15]
	v_lshl_add_u64 v[18:19], v[16:17], 0, v[18:19]
	global_store_dwordx4 v[18:19], v[10:13], off sc1
	v_add_u32_e32 v18, 8, v14
	ds_read2_b32 v[8:9], v51 offset0:8 offset1:41
	v_ashrrev_i32_e32 v19, 31, v18
	s_waitcnt lgkmcnt(0)
	v_cvt_pk_bf16_f32 v8, v8, v9
	ds_read2_b32 v[10:11], v51 offset0:74 offset1:107
	v_lshlrev_b64 v[18:19], 11, v[18:19]
	s_waitcnt lgkmcnt(0)
	v_cvt_pk_bf16_f32 v9, v10, v11
	ds_read2_b32 v[10:11], v51 offset0:140 offset1:173
	v_lshl_add_u64 v[18:19], v[16:17], 0, v[18:19]
	s_waitcnt lgkmcnt(0)
	v_cvt_pk_bf16_f32 v10, v10, v11
	ds_read2_b32 v[12:13], v51 offset0:206 offset1:239
	s_waitcnt lgkmcnt(0)
	v_cvt_pk_bf16_f32 v11, v12, v13
	global_store_dwordx4 v[18:19], v[8:11], off sc1
	v_add_u32_e32 v18, 16, v14
	ds_read2_b32 v[12:13], v51 offset0:16 offset1:49
	s_waitcnt lgkmcnt(0)
	v_cvt_pk_bf16_f32 v8, v12, v13
	ds_read2_b32 v[10:11], v51 offset0:82 offset1:115
	v_ashrrev_i32_e32 v19, 31, v18
	s_waitcnt lgkmcnt(0)
	v_cvt_pk_bf16_f32 v9, v10, v11
	ds_read2_b32 v[10:11], v51 offset0:148 offset1:181
	v_lshlrev_b64 v[18:19], 11, v[18:19]
	s_waitcnt lgkmcnt(0)
	v_cvt_pk_bf16_f32 v10, v10, v11
	ds_read2_b32 v[12:13], v51 offset0:214 offset1:247
	s_waitcnt lgkmcnt(0)
	v_cvt_pk_bf16_f32 v11, v12, v13
	v_lshl_add_u64 v[18:19], v[16:17], 0, v[18:19]
	ds_read2_b32 v[12:13], v51 offset0:24 offset1:57
	global_store_dwordx4 v[18:19], v[8:11], off sc1
	v_add_u32_e32 v14, 24, v14
	v_ashrrev_i32_e32 v15, 31, v14
	s_waitcnt lgkmcnt(0)
	v_cvt_pk_bf16_f32 v8, v12, v13
	ds_read2_b32 v[10:11], v51 offset0:90 offset1:123
	s_waitcnt lgkmcnt(0)
	v_cvt_pk_bf16_f32 v9, v10, v11
	ds_read2_b32 v[10:11], v51 offset0:156 offset1:189
	s_waitcnt lgkmcnt(0)
	v_cvt_pk_bf16_f32 v10, v10, v11
	ds_read2_b32 v[12:13], v51 offset0:222 offset1:255
	v_lshlrev_b64 v[14:15], 11, v[14:15]
	s_waitcnt lgkmcnt(0)
	v_cvt_pk_bf16_f32 v11, v12, v13
	v_lshl_add_u64 v[12:13], v[16:17], 0, v[14:15]
	global_store_dwordx4 v[12:13], v[8:11], off sc1
	s_waitcnt lgkmcnt(0)

; #define LAS __attribute__((address_space(3)))
; __device__ __forceinline__ unsigned pk2(float lo, float hi) { return pg8::cvt_pk_bf16(lo, hi); }
; template <int MAP>
; __device__ __forceinline__ void transpose_item(const float* W, int K, int N, bf16_t* WT, const float* gk, LAS float* scr, int item, int nblk, int lane) {
;     const int kb = item / nblk, nb = item % nblk, k0 = 64 * kb, n0 = 32 * nb;
;     const int src = MAP ? win_src_col(n0 + (lane & 31)) : n0 + (lane & 31);
;     float tv[32];
; #pragma unroll
;     for (int i = 0; i < 32; ++i) { const int kk = 2 * i + (lane >> 5); tv[i] = (src >= 0) ? __builtin_nontemporal_load(W + (size_t)(k0 + kk) * N + src) : 0.f; }
;     if (gk) {
; #pragma unroll
;         for (int i = 0; i < 32; ++i) tv[i] *= gk[k0 + 2 * i + (lane >> 5)]; }
; #pragma unroll
;     for (int i = 0; i < 32; ++i) scr[(2 * i + (lane >> 5)) * 33 + (lane & 31)] = tv[i];
;     asm volatile("s_waitcnt lgkmcnt(0)" ::: "memory");
;     const int c = lane & 7;
; #pragma unroll
;     for (int j = 0; j < 4; ++j) { const int n = (lane >> 3) + 8 * j; const LAS float* s = scr + (8 * c) * 33 + n;
;         u32x4 o; o.x = pk2(s[0 * 33], s[1 * 33]); o.y = pk2(s[2 * 33], s[3 * 33]); o.z = pk2(s[4 * 33], s[5 * 33]); o.w = pk2(s[6 * 33], s[7 * 33]);
;         *(u32x4*)(WT + (size_t)(n0 + n) * K + k0 + 8 * c) = o; }
;     asm volatile("s_waitcnt lgkmcnt(0)" ::: "memory");
; __device__ __forceinline__ void phase0(const Args& a, LAS unsigned char* lds) {
;     ...
;         if (r < I_C) { transpose_item<0>(a.in[6], 2048, 256, (bf16_t*)(ws + WS_W1T), nullptr, scr, r, 8, lane); continue; } r -= I_C;
;         transpose_item<0>(a.in[6] + (size_t)2048 * 256, 2048, 256, (bf16_t*)(ws + WS_W1T) + (size_t)256 * 2048, nullptr, scr, r, 8, lane);
.LBB0_20:
	v_cmp_lt_i32_e32 vcc, s20, v65
	s_and_saveexec_b64 s[12:13], vcc
	s_xor_b64 s[12:13], exec, s[12:13]
	s_cbranch_execz .LBB0_26
	v_and_b32_e32 v0, 0x7c0, v57
	v_and_b32_e32 v8, 0xe0, v55
	v_or_b32_e32 v10, v0, v48
	v_or_b32_e32 v9, v8, v47
	v_lshlrev_b32_e32 v10, 8, v10
	v_or_b32_e32 v11, v8, v50
	v_or_b32_e32 v12, v8, v52
	v_or_b32_e32 v13, v8, v53
	v_or_b32_e32 v8, v8, v54
	v_cmp_lt_u32_e32 vcc, s21, v65
	v_lshlrev_b32_e32 v14, 1, v0
	v_lshlrev_b32_e32 v0, 2, v9
	v_lshlrev_b32_e32 v18, 2, v10
	v_lshlrev_b32_e32 v16, 12, v11
	v_lshlrev_b32_e32 v12, 12, v12
	v_lshlrev_b32_e32 v10, 12, v13
	v_lshlrev_b32_e32 v8, 12, v8
	s_and_saveexec_b64 s[16:17], vcc
	s_xor_b64 s[16:17], exec, s[16:17]
	s_cbranch_execz .LBB0_23
	v_lshl_add_u64 v[20:21], s[2:3], 0, v[0:1]
	v_mov_b32_e32 v19, v1
	v_lshl_add_u64 v[18:19], v[20:21], 0, v[18:19]
	v_add_co_u32_e32 v20, vcc, 0x1000, v18
	s_nop 1
	v_addc_co_u32_e32 v21, vcc, 0, v19, vcc
	v_add_co_u32_e32 v22, vcc, 0x2000, v18
	s_nop 1
	v_addc_co_u32_e32 v23, vcc, 0, v19, vcc
	v_add_co_u32_e32 v24, vcc, 0x3000, v18
	s_nop 1
	v_addc_co_u32_e32 v25, vcc, 0, v19, vcc
	global_load_dword v0, v[18:19], off nt
	global_load_dword v9, v[18:19], off offset:2048 nt
	global_load_dword v11, v[20:21], off nt
	global_load_dword v13, v[20:21], off offset:2048 nt
	global_load_dword v15, v[22:23], off nt
	global_load_dword v17, v[22:23], off offset:2048 nt
	global_load_dword v28, v[24:25], off nt
	global_load_dword v29, v[24:25], off offset:2048 nt
	v_add_co_u32_e32 v20, vcc, 0x4000, v18
	s_nop 1
	v_addc_co_u32_e32 v21, vcc, 0, v19, vcc
	v_add_co_u32_e32 v22, vcc, 0x5000, v18
	s_nop 1
	v_addc_co_u32_e32 v23, vcc, 0, v19, vcc
	v_add_co_u32_e32 v24, vcc, 0x6000, v18
	s_nop 1
	v_addc_co_u32_e32 v25, vcc, 0, v19, vcc
	v_add_co_u32_e32 v26, vcc, 0x7000, v18
	s_nop 1
	v_addc_co_u32_e32 v27, vcc, 0, v19, vcc
	global_load_dword v30, v[20:21], off nt
	global_load_dword v31, v[20:21], off offset:2048 nt
	global_load_dword v32, v[22:23], off nt
	global_load_dword v33, v[22:23], off offset:2048 nt
	global_load_dword v34, v[24:25], off nt
	global_load_dword v35, v[24:25], off offset:2048 nt
	global_load_dword v36, v[26:27], off nt
	global_load_dword v37, v[26:27], off offset:2048 nt
	v_add_co_u32_e32 v20, vcc, 0x8000, v18
	s_nop 1
	v_addc_co_u32_e32 v21, vcc, 0, v19, vcc
	v_add_co_u32_e32 v22, vcc, 0x9000, v18
	s_nop 1
	v_addc_co_u32_e32 v23, vcc, 0, v19, vcc
	v_add_co_u32_e32 v24, vcc, 0xa000, v18
	s_nop 1
	v_addc_co_u32_e32 v25, vcc, 0, v19, vcc
	v_add_co_u32_e32 v26, vcc, 0xb000, v18
	s_nop 1
	v_addc_co_u32_e32 v27, vcc, 0, v19, vcc
	global_load_dword v38, v[20:21], off nt
	global_load_dword v39, v[20:21], off offset:2048 nt
	global_load_dword v40, v[22:23], off nt
	global_load_dword v41, v[22:23], off offset:2048 nt
	global_load_dword v42, v[24:25], off nt
	global_load_dword v43, v[24:25], off offset:2048 nt
	global_load_dword v44, v[26:27], off nt
	s_nop 0
	global_load_dword v26, v[26:27], off offset:2048 nt
	v_add_co_u32_e32 v20, vcc, 0xc000, v18
	s_nop 1
	v_addc_co_u32_e32 v21, vcc, 0, v19, vcc
	v_add_co_u32_e32 v22, vcc, 0xd000, v18
	s_nop 1
	v_addc_co_u32_e32 v23, vcc, 0, v19, vcc
	v_add_co_u32_e32 v24, vcc, 0xe000, v18
	s_nop 1
	v_addc_co_u32_e32 v25, vcc, 0, v19, vcc
	v_add_co_u32_e32 v18, vcc, 0xf000, v18
	s_nop 1
	v_addc_co_u32_e32 v19, vcc, 0, v19, vcc
	global_load_dword v27, v[20:21], off nt
	s_nop 0
	global_load_dword v20, v[20:21], off offset:2048 nt
	s_nop 0
	global_load_dword v21, v[22:23], off nt
	s_nop 0
	global_load_dword v22, v[22:23], off offset:2048 nt
	s_nop 0
	global_load_dword v23, v[24:25], off nt
	s_nop 0
	global_load_dword v24, v[24:25], off offset:2048 nt
	s_nop 0
	global_load_dword v25, v[18:19], off nt
	s_nop 0
	global_load_dword v18, v[18:19], off offset:2048 nt
	s_waitcnt vmcnt(30)
	ds_write2_b32 v49, v0, v9 offset1:66
	s_waitcnt vmcnt(28)
	ds_write2_b32 v49, v11, v13 offset0:132 offset1:198
	s_waitcnt vmcnt(26)
	ds_write2_b32 v58, v15, v17 offset0:8 offset1:74
	s_waitcnt vmcnt(24)
	ds_write2_b32 v58, v28, v29 offset0:140 offset1:206
	s_waitcnt vmcnt(22)
	ds_write2_b32 v59, v30, v31 offset0:16 offset1:82
	s_waitcnt vmcnt(20)
	ds_write2_b32 v59, v32, v33 offset0:148 offset1:214
	s_waitcnt vmcnt(18)
	ds_write2_b32 v60, v34, v35 offset0:24 offset1:90
	s_waitcnt vmcnt(16)
	ds_write2_b32 v60, v36, v37 offset0:156 offset1:222
	s_waitcnt vmcnt(14)
	ds_write2_b32 v61, v38, v39 offset0:32 offset1:98
	s_waitcnt vmcnt(12)
	ds_write2_b32 v61, v40, v41 offset0:164 offset1:230
	s_waitcnt vmcnt(10)
	ds_write2_b32 v62, v42, v43 offset0:40 offset1:106
	s_waitcnt vmcnt(8)
	ds_write2_b32 v62, v44, v26 offset0:172 offset1:238
	s_waitcnt vmcnt(6)
	ds_write2_b32 v63, v27, v20 offset0:48 offset1:114
	s_waitcnt vmcnt(4)
	ds_write2_b32 v63, v21, v22 offset0:180 offset1:246
	s_waitcnt vmcnt(2)
	ds_write2_b32 v64, v23, v24 offset0:56 offset1:122
	s_waitcnt vmcnt(0)
	ds_write2_b32 v64, v25, v18 offset0:188 offset1:254
	s_waitcnt lgkmcnt(0)
	ds_read2_b32 v[18:19], v51 offset1:33
	s_waitcnt lgkmcnt(0)
	v_cvt_pk_bf16_f32 v18, v18, v19
	ds_read2_b32 v[20:21], v51 offset0:66 offset1:99
	v_mov_b32_e32 v15, v1
	s_waitcnt lgkmcnt(0)
	v_cvt_pk_bf16_f32 v19, v20, v21
	ds_read2_b32 v[20:21], v51 offset0:132 offset1:165
	v_lshl_add_u64 v[24:25], v[2:3], 0, v[14:15]
	v_mov_b32_e32 v17, v1
	s_waitcnt lgkmcnt(0)
	v_cvt_pk_bf16_f32 v20, v20, v21
	ds_read2_b32 v[22:23], v51 offset0:198 offset1:231
	v_lshl_add_u64 v[14:15], v[24:25], 0, v[16:17]
	s_waitcnt lgkmcnt(0)
	v_cvt_pk_bf16_f32 v21, v22, v23
	ds_read2_b32 v[22:23], v51 offset0:8 offset1:41
	global_store_dwordx4 v[14:15], v[18:21], off sc1
	s_waitcnt lgkmcnt(0)
; #define LAS __attribute__((address_space(3)))
; __device__ __forceinline__ unsigned pk2(float lo, float hi) { return pg8::cvt_pk_bf16(lo, hi); }
; template <int MAP>
; __device__ __forceinline__ void transpose_item(const float* W, int K, int N, bf16_t* WT, const float* gk, LAS float* scr, int item, int nblk, int lane) {
;     ...
;     const int c = lane & 7;
; #pragma unroll
;     for (int j = 0; j < 4; ++j) { const int n = (lane >> 3) + 8 * j; const LAS float* s = scr + (8 * c) * 33 + n;
;         u32x4 o; o.x = pk2(s[0 * 33], s[1 * 33]); o.y = pk2(s[2 * 33], s[3 * 33]); o.z = pk2(s[4 * 33], s[5 * 33]); o.w = pk2(s[6 * 33], s[7 * 33]);
;         *(u32x4*)(WT + (size_t)(n0 + n) * K + k0 + 8 * c) = o; }
;     asm volatile("s_waitcnt lgkmcnt(0)" ::: "memory");
	v_cvt_pk_bf16_f32 v14, v22, v23
	ds_read2_b32 v[16:17], v51 offset0:74 offset1:107
	s_waitcnt lgkmcnt(0)
	v_cvt_pk_bf16_f32 v15, v16, v17
	ds_read2_b32 v[16:17], v51 offset0:140 offset1:173
	v_mov_b32_e32 v13, v1
	s_waitcnt lgkmcnt(0)
	v_cvt_pk_bf16_f32 v16, v16, v17
	ds_read2_b32 v[18:19], v51 offset0:206 offset1:239
	v_lshl_add_u64 v[12:13], v[24:25], 0, v[12:13]
	s_waitcnt lgkmcnt(0)
	v_cvt_pk_bf16_f32 v17, v18, v19
	ds_read2_b32 v[18:19], v51 offset0:16 offset1:49
	global_store_dwordx4 v[12:13], v[14:17], off sc1
	s_waitcnt lgkmcnt(0)
	v_cvt_pk_bf16_f32 v12, v18, v19
	ds_read2_b32 v[14:15], v51 offset0:82 offset1:115
	s_waitcnt lgkmcnt(0)
	v_cvt_pk_bf16_f32 v13, v14, v15
	ds_read2_b32 v[14:15], v51 offset0:148 offset1:181
	v_mov_b32_e32 v11, v1
	s_waitcnt lgkmcnt(0)
	v_cvt_pk_bf16_f32 v14, v14, v15
	ds_read2_b32 v[16:17], v51 offset0:214 offset1:247
	v_lshl_add_u64 v[10:11], v[24:25], 0, v[10:11]
	s_waitcnt lgkmcnt(0)
	v_cvt_pk_bf16_f32 v15, v16, v17
	ds_read2_b32 v[16:17], v51 offset0:24 offset1:57
	global_store_dwordx4 v[10:11], v[12:15], off sc1
	s_waitcnt lgkmcnt(0)
	v_cvt_pk_bf16_f32 v10, v16, v17
	ds_read2_b32 v[12:13], v51 offset0:90 offset1:123
	v_mov_b32_e32 v9, v1
	s_waitcnt lgkmcnt(0)
	v_cvt_pk_bf16_f32 v11, v12, v13
	ds_read2_b32 v[12:13], v51 offset0:156 offset1:189
	v_lshl_add_u64 v[8:9], v[24:25], 0, v[8:9]
	s_waitcnt lgkmcnt(0)
	v_cvt_pk_bf16_f32 v12, v12, v13
	ds_read2_b32 v[14:15], v51 offset0:222 offset1:255
	s_waitcnt lgkmcnt(0)
	v_cvt_pk_bf16_f32 v13, v14, v15
	global_store_dwordx4 v[8:9], v[10:13], off sc1
	s_waitcnt lgkmcnt(0)
; #define LAS __attribute__((address_space(3)))
; __device__ __forceinline__ unsigned pk2(float lo, float hi) { return pg8::cvt_pk_bf16(lo, hi); }
; template <int MAP>
; __device__ __forceinline__ void transpose_item(const float* W, int K, int N, bf16_t* WT, const float* gk, LAS float* scr, int item, int nblk, int lane) {
;     const int kb = item / nblk, nb = item % nblk, k0 = 64 * kb, n0 = 32 * nb;
;     const int src = MAP ? win_src_col(n0 + (lane & 31)) : n0 + (lane & 31);
;     float tv[32];
; #pragma unroll
;     for (int i = 0; i < 32; ++i) { const int kk = 2 * i + (lane >> 5); tv[i] = (src >= 0) ? __builtin_nontemporal_load(W + (size_t)(k0 + kk) * N + src) : 0.f; }
;     if (gk) {
; #pragma unroll
;         for (int i = 0; i < 32; ++i) tv[i] *= gk[k0 + 2 * i + (lane >> 5)]; }
; #pragma unroll
;     for (int i = 0; i < 32; ++i) scr[(2 * i + (lane >> 5)) * 33 + (lane & 31)] = tv[i];
;     asm volatile("s_waitcnt lgkmcnt(0)" ::: "memory");
;     const int c = lane & 7;
; #pragma unroll
;     for (int j = 0; j < 4; ++j) { const int n = (lane >> 3) + 8 * j; const LAS float* s = scr + (8 * c) * 33 + n;
;         u32x4 o; o.x = pk2(s[0 * 33], s[1 * 33]); o.y = pk2(s[2 * 33], s[3 * 33]); o.z = pk2(s[4 * 33], s[5 * 33]); o.w = pk2(s[6 * 33], s[7 * 33]);
;         *(u32x4*)(WT + (size_t)(n0 + n) * K + k0 + 8 * c) = o; }
;     asm volatile("s_waitcnt lgkmcnt(0)" ::: "memory");
; __device__ __forceinline__ void phase0(const Args& a, LAS unsigned char* lds) {
;     ...
;         if (r < I_C) { transpose_item<0>(a.in[6], 2048, 256, (bf16_t*)(ws + WS_W1T), nullptr, scr, r, 8, lane); continue; } r -= I_C;
.LBB0_23:
	s_andn2_saveexec_b64 s[16:17], s[16:17]
	s_cbranch_execz .LBB0_25
	v_lshl_add_u64 v[20:21], s[84:85], 0, v[0:1]
	v_mov_b32_e32 v19, v1
	v_lshl_add_u64 v[18:19], v[20:21], 0, v[18:19]
	v_add_co_u32_e32 v20, vcc, 0x1000, v18
	s_nop 1
	v_addc_co_u32_e32 v21, vcc, 0, v19, vcc
	v_add_co_u32_e32 v22, vcc, 0x2000, v18
	s_nop 1
	v_addc_co_u32_e32 v23, vcc, 0, v19, vcc
	v_add_co_u32_e32 v24, vcc, 0x3000, v18
	s_nop 1
	v_addc_co_u32_e32 v25, vcc, 0, v19, vcc
	global_load_dword v0, v[18:19], off nt
	global_load_dword v9, v[18:19], off offset:2048 nt
	global_load_dword v11, v[20:21], off nt
	global_load_dword v13, v[20:21], off offset:2048 nt
	global_load_dword v15, v[22:23], off nt
	global_load_dword v17, v[22:23], off offset:2048 nt
	global_load_dword v28, v[24:25], off nt
	global_load_dword v29, v[24:25], off offset:2048 nt
	v_add_co_u32_e32 v20, vcc, 0x4000, v18
	s_nop 1
	v_addc_co_u32_e32 v21, vcc, 0, v19, vcc
	v_add_co_u32_e32 v22, vcc, 0x5000, v18
	s_nop 1
	v_addc_co_u32_e32 v23, vcc, 0, v19, vcc
	v_add_co_u32_e32 v24, vcc, 0x6000, v18
	s_nop 1
	v_addc_co_u32_e32 v25, vcc, 0, v19, vcc
	v_add_co_u32_e32 v26, vcc, 0x7000, v18
	s_nop 1
	v_addc_co_u32_e32 v27, vcc, 0, v19, vcc
	global_load_dword v30, v[20:21], off nt
	global_load_dword v31, v[20:21], off offset:2048 nt
	global_load_dword v32, v[22:23], off nt
	global_load_dword v33, v[22:23], off offset:2048 nt
	global_load_dword v34, v[24:25], off nt
	global_load_dword v35, v[24:25], off offset:2048 nt
	global_load_dword v36, v[26:27], off nt
	global_load_dword v37, v[26:27], off offset:2048 nt
	v_add_co_u32_e32 v20, vcc, 0x8000, v18
	s_nop 1
	v_addc_co_u32_e32 v21, vcc, 0, v19, vcc
	v_add_co_u32_e32 v22, vcc, 0x9000, v18
	s_nop 1
	v_addc_co_u32_e32 v23, vcc, 0, v19, vcc
	v_add_co_u32_e32 v24, vcc, 0xa000, v18
	s_nop 1
	v_addc_co_u32_e32 v25, vcc, 0, v19, vcc
	v_add_co_u32_e32 v26, vcc, 0xb000, v18
	s_nop 1
	v_addc_co_u32_e32 v27, vcc, 0, v19, vcc
	global_load_dword v38, v[20:21], off nt
	global_load_dword v39, v[20:21], off offset:2048 nt
	global_load_dword v40, v[22:23], off nt
	global_load_dword v41, v[22:23], off offset:2048 nt
	global_load_dword v42, v[24:25], off nt
	global_load_dword v43, v[24:25], off offset:2048 nt
	global_load_dword v44, v[26:27], off nt
	s_nop 0
	global_load_dword v26, v[26:27], off offset:2048 nt
	v_add_co_u32_e32 v20, vcc, 0xc000, v18
	s_nop 1
	v_addc_co_u32_e32 v21, vcc, 0, v19, vcc
	v_add_co_u32_e32 v22, vcc, 0xd000, v18
	s_nop 1
	v_addc_co_u32_e32 v23, vcc, 0, v19, vcc
	v_add_co_u32_e32 v24, vcc, 0xe000, v18
	s_nop 1
	v_addc_co_u32_e32 v25, vcc, 0, v19, vcc
	v_add_co_u32_e32 v18, vcc, 0xf000, v18
	s_nop 1
	v_addc_co_u32_e32 v19, vcc, 0, v19, vcc
	global_load_dword v27, v[20:21], off nt
	s_nop 0
	global_load_dword v20, v[20:21], off offset:2048 nt
	s_nop 0
	global_load_dword v21, v[22:23], off nt
	s_nop 0
	global_load_dword v22, v[22:23], off offset:2048 nt
	s_nop 0
	global_load_dword v23, v[24:25], off nt
	s_nop 0
	global_load_dword v24, v[24:25], off offset:2048 nt
	s_nop 0
	global_load_dword v25, v[18:19], off nt
	s_nop 0
	global_load_dword v18, v[18:19], off offset:2048 nt
	s_waitcnt vmcnt(30)
	ds_write2_b32 v49, v0, v9 offset1:66
	s_waitcnt vmcnt(28)
	ds_write2_b32 v49, v11, v13 offset0:132 offset1:198
	s_waitcnt vmcnt(26)
	ds_write2_b32 v58, v15, v17 offset0:8 offset1:74
	s_waitcnt vmcnt(24)
	ds_write2_b32 v58, v28, v29 offset0:140 offset1:206
	s_waitcnt vmcnt(22)
	ds_write2_b32 v59, v30, v31 offset0:16 offset1:82
	s_waitcnt vmcnt(20)
	ds_write2_b32 v59, v32, v33 offset0:148 offset1:214
	s_waitcnt vmcnt(18)
	ds_write2_b32 v60, v34, v35 offset0:24 offset1:90
	s_waitcnt vmcnt(16)
	ds_write2_b32 v60, v36, v37 offset0:156 offset1:222
	s_waitcnt vmcnt(14)
	ds_write2_b32 v61, v38, v39 offset0:32 offset1:98
	s_waitcnt vmcnt(12)
	ds_write2_b32 v61, v40, v41 offset0:164 offset1:230
	s_waitcnt vmcnt(10)
	ds_write2_b32 v62, v42, v43 offset0:40 offset1:106
	s_waitcnt vmcnt(8)
	ds_write2_b32 v62, v44, v26 offset0:172 offset1:238
	s_waitcnt vmcnt(6)
	ds_write2_b32 v63, v27, v20 offset0:48 offset1:114
	s_waitcnt vmcnt(4)
	ds_write2_b32 v63, v21, v22 offset0:180 offset1:246
	s_waitcnt vmcnt(2)
	ds_write2_b32 v64, v23, v24 offset0:56 offset1:122
	s_waitcnt vmcnt(0)
	ds_write2_b32 v64, v25, v18 offset0:188 offset1:254
	s_waitcnt lgkmcnt(0)
	ds_read2_b32 v[18:19], v51 offset1:33
	s_waitcnt lgkmcnt(0)
	v_cvt_pk_bf16_f32 v18, v18, v19
	ds_read2_b32 v[20:21], v51 offset0:66 offset1:99
	v_mov_b32_e32 v15, v1
	s_waitcnt lgkmcnt(0)
	v_cvt_pk_bf16_f32 v19, v20, v21
	ds_read2_b32 v[20:21], v51 offset0:132 offset1:165
	v_lshl_add_u64 v[24:25], v[4:5], 0, v[14:15]
	v_mov_b32_e32 v17, v1
	s_waitcnt lgkmcnt(0)
	v_cvt_pk_bf16_f32 v20, v20, v21
	ds_read2_b32 v[22:23], v51 offset0:198 offset1:231
	v_lshl_add_u64 v[14:15], v[24:25], 0, v[16:17]
	s_waitcnt lgkmcnt(0)
	v_cvt_pk_bf16_f32 v21, v22, v23
	ds_read2_b32 v[22:23], v51 offset0:8 offset1:41
	global_store_dwordx4 v[14:15], v[18:21], off sc1
	s_waitcnt lgkmcnt(0)
	v_cvt_pk_bf16_f32 v14, v22, v23
	ds_read2_b32 v[16:17], v51 offset0:74 offset1:107
	s_waitcnt lgkmcnt(0)
	v_cvt_pk_bf16_f32 v15, v16, v17
	ds_read2_b32 v[16:17], v51 offset0:140 offset1:173
	v_mov_b32_e32 v13, v1
	s_waitcnt lgkmcnt(0)
	v_cvt_pk_bf16_f32 v16, v16, v17
	ds_read2_b32 v[18:19], v51 offset0:206 offset1:239
	v_lshl_add_u64 v[12:13], v[24:25], 0, v[12:13]
	s_waitcnt lgkmcnt(0)
	v_cvt_pk_bf16_f32 v17, v18, v19
	ds_read2_b32 v[18:19], v51 offset0:16 offset1:49
	global_store_dwordx4 v[12:13], v[14:17], off sc1
	s_waitcnt lgkmcnt(0)
	v_cvt_pk_bf16_f32 v12, v18, v19
	ds_read2_b32 v[14:15], v51 offset0:82 offset1:115
	s_waitcnt lgkmcnt(0)
	v_cvt_pk_bf16_f32 v13, v14, v15
	ds_read2_b32 v[14:15], v51 offset0:148 offset1:181
	v_mov_b32_e32 v11, v1
	s_waitcnt lgkmcnt(0)
	v_cvt_pk_bf16_f32 v14, v14, v15
	ds_read2_b32 v[16:17], v51 offset0:214 offset1:247
	v_lshl_add_u64 v[10:11], v[24:25], 0, v[10:11]
	s_waitcnt lgkmcnt(0)
	v_cvt_pk_bf16_f32 v15, v16, v17
	ds_read2_b32 v[16:17], v51 offset0:24 offset1:57
	global_store_dwordx4 v[10:11], v[12:15], off sc1
	s_waitcnt lgkmcnt(0)
	v_cvt_pk_bf16_f32 v10, v16, v17
	ds_read2_b32 v[12:13], v51 offset0:90 offset1:123
	v_mov_b32_e32 v9, v1
	s_waitcnt lgkmcnt(0)
	v_cvt_pk_bf16_f32 v11, v12, v13
	ds_read2_b32 v[12:13], v51 offset0:156 offset1:189
	v_lshl_add_u64 v[8:9], v[24:25], 0, v[8:9]
	s_waitcnt lgkmcnt(0)
	v_cvt_pk_bf16_f32 v12, v12, v13
	ds_read2_b32 v[14:15], v51 offset0:222 offset1:255
	s_waitcnt lgkmcnt(0)
	v_cvt_pk_bf16_f32 v13, v14, v15
	global_store_dwordx4 v[8:9], v[10:13], off sc1
	s_waitcnt lgkmcnt(0)

; __device__ __forceinline__ unsigned pk2(float lo, float hi) { return pg8::cvt_pk_bf16(lo, hi); }
; __device__ __forceinline__ void phase0(const Args& a, LAS unsigned char* lds) {
;     ...
;         for (int m = gw; m < T; m += 2 * NGW) {
;             const int m2 = m + NGW;
;             const bool has2 = m2 < T;
;             const f32x4* xr = (const f32x4*)(x + (size_t)m * DM) + lane;
;             const f32x4* xr2 = (const f32x4*)(x + (size_t)(has2 ? m2 : m) * DM) + lane;
;             f32x4 v[4], u[4]; float s = 0.f, s2 = 0.f;
; #pragma unroll
;             for (int j = 0; j < 4; ++j) { v[j] = __builtin_nontemporal_load(xr + 64 * j); u[j] = __builtin_nontemporal_load(xr2 + 64 * j); }
; #pragma unroll
;             for (int j = 0; j < 4; ++j) { s += (v[j].x * v[j].x + v[j].y * v[j].y) + (v[j].z * v[j].z + v[j].w * v[j].w); s2 += (u[j].x * u[j].x + u[j].y * u[j].y) + (u[j].z * u[j].z + u[j].w * u[j].w); }
;             s = wave_sum(s); s2 = wave_sum(s2);
;             if (lane == 0) { rinv1[m] = rsqrtf(s * (1.f / 1024.f) + EPS); if (has2) rinv1[m2] = rsqrtf(s2 * (1.f / 1024.f) + EPS); }
;             unsigned long long* o8 = (unsigned long long*)(xb + (size_t)m * DM) + lane;
; #pragma unroll
;             for (int j = 0; j < 4; ++j) o8[64 * j] = (unsigned long long)pk2(v[j].x, v[j].y) | ((unsigned long long)pk2(v[j].z, v[j].w) << 32);
;             if (has2) { unsigned long long* o82 = (unsigned long long*)(xb + (size_t)m2 * DM) + lane;
; #pragma unroll
;                 for (int j = 0; j < 4; ++j) o82[64 * j] = (unsigned long long)pk2(u[j].x, u[j].y) | ((unsigned long long)pk2(u[j].z, u[j].w) << 32); }
;         }
.LBB0_102:
	v_ashrrev_i32_e32 v39, 31, v38
	v_lshlrev_b64 v[0:1], 12, v[38:39]
	v_add_u32_e32 v36, s6, v38
	v_lshl_add_u64 v[0:1], v[32:33], 0, v[0:1]
	v_cmp_gt_i32_e64 s[2:3], s14, v36
	global_load_dwordx4 v[28:31], v[0:1], off nt
	global_load_dwordx4 v[24:27], v[0:1], off offset:1024 nt
	global_load_dwordx4 v[20:23], v[0:1], off offset:2048 nt
	global_load_dwordx4 v[16:19], v[0:1], off offset:3072 nt
	v_cndmask_b32_e64 v0, v38, v36, s[2:3]
	v_ashrrev_i32_e32 v1, 31, v0
	v_lshlrev_b64 v[0:1], 12, v[0:1]
	v_lshl_add_u64 v[0:1], v[32:33], 0, v[0:1]
	global_load_dwordx4 v[12:15], v[0:1], off nt
	global_load_dwordx4 v[8:11], v[0:1], off offset:1024 nt
	global_load_dwordx4 v[4:7], v[0:1], off offset:2048 nt
	s_nop 0
	global_load_dwordx4 v[0:3], v[0:1], off offset:3072 nt
	s_waitcnt vmcnt(7)
	v_mul_f32_e32 v37, v29, v29
	v_mul_f32_e32 v40, v31, v31
	s_waitcnt vmcnt(6) lgkmcnt(1)
	v_mul_f32_e32 v41, v25, v25
	s_waitcnt lgkmcnt(0)
	v_mul_f32_e32 v50, v27, v27
	s_waitcnt vmcnt(5)
	v_mul_f32_e32 v51, v21, v21
	v_mul_f32_e32 v52, v23, v23
	v_fmac_f32_e32 v37, v28, v28
	v_fmac_f32_e32 v40, v30, v30
	v_fmac_f32_e32 v41, v24, v24
	v_fmac_f32_e32 v50, v26, v26
	s_waitcnt vmcnt(4)
	v_mul_f32_e32 v53, v17, v17
	v_mul_f32_e32 v54, v19, v19
	v_fmac_f32_e32 v51, v20, v20
	v_fmac_f32_e32 v52, v22, v22
	v_add_f32_e32 v37, v37, v40
	s_waitcnt vmcnt(3)
	v_mul_f32_e32 v40, v13, v13
	v_mul_f32_e32 v55, v15, v15
	v_add_f32_e32 v41, v41, v50
	s_waitcnt vmcnt(2)
	v_mul_f32_e32 v50, v9, v9
	v_mul_f32_e32 v56, v11, v11
	v_fmac_f32_e32 v53, v16, v16
	v_fmac_f32_e32 v54, v18, v18
	v_add_f32_e32 v51, v51, v52
	s_waitcnt vmcnt(1)
	v_mul_f32_e32 v52, v5, v5
	v_mul_f32_e32 v57, v7, v7
	v_fmac_f32_e32 v40, v12, v12
	v_fmac_f32_e32 v55, v14, v14
	v_fmac_f32_e32 v50, v8, v8
	v_fmac_f32_e32 v56, v10, v10
	v_add_f32_e32 v53, v53, v54
	s_waitcnt vmcnt(0)
	v_mul_f32_e32 v54, v1, v1
	v_mul_f32_e32 v58, v3, v3
	v_add_f32_e32 v37, v37, v41
	v_fmac_f32_e32 v52, v4, v4
	v_fmac_f32_e32 v57, v6, v6
	v_add_f32_e32 v40, v40, v55
	v_add_f32_e32 v41, v50, v56
	v_fmac_f32_e32 v54, v0, v0
	v_fmac_f32_e32 v58, v2, v2
	v_add_f32_e32 v50, v52, v57
	v_add_f32_e32 v40, v40, v41
	v_add_f32_e32 v37, v37, v51
	v_add_f32_e32 v51, v54, v58
	v_add_f32_e32 v40, v40, v50
	v_add_f32_e32 v37, v37, v53
	v_add_f32_e32 v40, v40, v51
	ds_bpermute_b32 v41, v42, v37
	ds_bpermute_b32 v50, v42, v40
	s_waitcnt lgkmcnt(1)
	v_add_f32_e32 v37, v37, v41
	s_waitcnt lgkmcnt(0)
	v_add_f32_e32 v40, v40, v50
	ds_bpermute_b32 v41, v43, v37
	ds_bpermute_b32 v50, v43, v40
	s_waitcnt lgkmcnt(1)
	v_add_f32_e32 v37, v37, v41
	s_waitcnt lgkmcnt(0)
	v_add_f32_e32 v40, v40, v50
	ds_bpermute_b32 v41, v44, v37
	ds_bpermute_b32 v50, v44, v40
	s_waitcnt lgkmcnt(1)
	v_add_f32_e32 v37, v37, v41
	s_waitcnt lgkmcnt(0)
	v_add_f32_e32 v40, v40, v50
	ds_bpermute_b32 v41, v45, v37
	ds_bpermute_b32 v50, v45, v40
	s_waitcnt lgkmcnt(1)
	v_add_f32_e32 v37, v37, v41
	s_waitcnt lgkmcnt(0)
	v_add_f32_e32 v50, v40, v50
	ds_bpermute_b32 v41, v47, v37
	ds_bpermute_b32 v51, v47, v50
	s_waitcnt lgkmcnt(1)
	v_add_f32_e32 v40, v37, v41
	s_waitcnt lgkmcnt(0)
	v_add_f32_e32 v37, v50, v51
	ds_bpermute_b32 v41, v48, v40
	ds_bpermute_b32 v50, v48, v37
	s_and_saveexec_b64 s[16:17], vcc
	s_cbranch_execz .LBB0_105
	s_waitcnt lgkmcnt(1)
	v_add_f32_e32 v40, v40, v41
	v_fmamk_f32 v40, v40, 0x3a800000, v49
	v_mul_f32_e32 v41, 0x4b800000, v40
	v_cmp_gt_f32_e64 s[0:1], s15, v40
	s_nop 1
	v_cndmask_b32_e64 v40, v40, v41, s[0:1]
	v_rsq_f32_e32 v40, v40
	s_nop 0
	v_mul_f32_e32 v41, 0x45800000, v40
	v_cndmask_b32_e64 v51, v40, v41, s[0:1]
	v_lshl_add_u64 v[40:41], v[38:39], 2, s[10:11]
	global_store_dword v[40:41], v51, off sc1
	s_and_b64 exec, exec, s[2:3]
	s_cbranch_execz .LBB0_105
	s_waitcnt lgkmcnt(0)
	v_add_f32_e32 v37, v37, v50
	v_fmamk_f32 v37, v37, 0x3a800000, v49
	v_mul_f32_e32 v50, 0x4b800000, v37
	v_cmp_gt_f32_e64 s[0:1], s15, v37
	v_lshl_add_u64 v[40:41], s[6:7], 2, v[40:41]
	s_nop 0
	v_cndmask_b32_e64 v37, v37, v50, s[0:1]
	v_rsq_f32_e32 v37, v37
	s_nop 0
	v_mul_f32_e32 v50, 0x45800000, v37
	v_cndmask_b32_e64 v37, v37, v50, s[0:1]
	global_store_dword v[40:41], v37, off sc1
.LBB0_105:
	s_or_b64 exec, exec, s[16:17]
	v_lshlrev_b64 v[38:39], 10, v[38:39]
	v_lshl_add_u64 v[38:39], v[38:39], 1, v[34:35]
	v_cvt_pk_bf16_f32 v28, v28, v29
	v_cvt_pk_bf16_f32 v29, v30, v31
	global_store_dwordx2 v[38:39], v[28:29], off sc1
	v_cvt_pk_bf16_f32 v24, v24, v25
	v_cvt_pk_bf16_f32 v25, v26, v27
	global_store_dwordx2 v[38:39], v[24:25], off offset:512 sc1
	v_cvt_pk_bf16_f32 v20, v20, v21
	v_cvt_pk_bf16_f32 v21, v22, v23
	global_store_dwordx2 v[38:39], v[20:21], off offset:1024 sc1
	v_cvt_pk_bf16_f32 v16, v16, v17
	v_cvt_pk_bf16_f32 v17, v18, v19
	global_store_dwordx2 v[38:39], v[16:17], off offset:1536 sc1
	s_and_saveexec_b64 s[0:1], s[2:3]
	s_cbranch_execz .LBB0_101
	v_ashrrev_i32_e32 v37, 31, v36
	v_lshlrev_b64 v[16:17], 11, v[36:37]
	v_lshl_add_u64 v[16:17], v[34:35], 0, v[16:17]
	v_cvt_pk_bf16_f32 v12, v12, v13
	v_cvt_pk_bf16_f32 v13, v14, v15
	global_store_dwordx2 v[16:17], v[12:13], off sc1
	v_cvt_pk_bf16_f32 v8, v8, v9
	v_cvt_pk_bf16_f32 v9, v10, v11
	global_store_dwordx2 v[16:17], v[8:9], off offset:512 sc1
	v_cvt_pk_bf16_f32 v4, v4, v5
	v_cvt_pk_bf16_f32 v5, v6, v7
	global_store_dwordx2 v[16:17], v[4:5], off offset:1024 sc1
	v_cvt_pk_bf16_f32 v0, v0, v1
	v_cvt_pk_bf16_f32 v1, v2, v3
	global_store_dwordx2 v[16:17], v[0:1], off offset:1536 sc1
	s_branch .LBB0_101

; __device__ __forceinline__ unsigned f2bf(float f) { unsigned u = __float_as_uint(f); return (u + 0x7fffu + ((u >> 16) & 1u)) >> 16; }
; __device__ __forceinline__ void phase0(const Args& a, LAS unsigned char* lds) {
;     ...
;         bf16_t* Wsp = (bf16_t*)(ws + WS_WSP); const float* spw = a.in[9];
;         for (int idx = blockIdx.x * 512 + tid; idx < 8 * 128 * 128; idx += gridDim.x * 512) { const int tq = (idx >> 7) & 127, sq = idx & 127; Wsp[idx] = (bf16_t)f2bf(sq <= tq ? spw[idx] : 0.f); }
;     }
.LBB0_109:
	s_or_b64 exec, exec, s[8:9]
	s_waitcnt vmcnt(0)
	v_bfe_u32 v4, v3, 16, 1
	v_add3_u32 v3, v3, v4, s11
	v_lshl_add_u64 v[4:5], v[0:1], 1, s[2:3]
	v_add_u32_e32 v0, s10, v0
	v_cmp_lt_i32_e32 vcc, s12, v0
	s_or_b64 s[6:7], vcc, s[6:7]
	global_store_short_d16_hi v[4:5], v3, off sc1
	s_andn2_b64 exec, exec, s[6:7]
	s_cbranch_execz .LBB0_112

; __device__ __forceinline__ void phase0(const Args& a, LAS unsigned char* lds) {
;     ...
;         if ((gw & 3) == 0 && (gw >> 2) < 512) {
;             const int item = gw >> 2, kv = item >> 8, cg4 = (item >> 6) & 3, kch = item & 63;
;             const float* pe = a.in[5] + kv * 2048 + kch * 32; const float* w1 = a.in[6] + ((size_t)kv * 2048 + kch * 32) * 256 + cg4 * 64 + lane;
;             float wv[32];
; #pragma unroll
;             for (int k = 0; k < 32; ++k) wv[k] = w1[(size_t)k * 256];
;             float acc = 0.f;
; #pragma unroll
;             for (int k = 0; k < 32; ++k) acc += pe[k] * wv[k];
;             ((float*)(ws + WS_C1P))[kch * 512 + kv * 256 + cg4 * 64 + lane] = acc;
;         }
.LBB0_112:
	s_or_b64 exec, exec, s[0:1]
	v_and_b32_e32 v0, 0xc0, v184
	v_cmp_eq_u32_e32 vcc, 0, v0
	s_and_saveexec_b64 s[0:1], vcc
	s_cbranch_execz .LBB0_115
	v_ashrrev_i32_e32 v0, 2, v46
	s_movk_i32 s2, 0x200
	v_cmp_gt_i32_e32 vcc, s2, v0
	s_and_b64 exec, exec, vcc
	s_cbranch_execz .LBB0_115
	v_ashrrev_i32_e32 v32, 10, v46
	v_ashrrev_i32_e32 v33, 31, v32
	v_bfe_u32 v48, v46, 2, 6
	v_lshlrev_b64 v[4:5], 21, v[32:33]
	v_lshl_add_u64 v[4:5], s[84:85], 0, v[4:5]
	v_lshlrev_b32_e32 v6, 15, v48
	v_mov_b32_e32 v7, 0
	v_lshl_add_u64 v[4:5], v[4:5], 0, v[6:7]
	v_lshrrev_b32_e32 v6, 2, v46
	v_and_b32_e32 v33, 0xc0, v6
	v_lshlrev_b32_e32 v6, 2, v33
	v_lshl_add_u64 v[4:5], v[4:5], 0, v[6:7]
	v_lshlrev_b32_e32 v6, 2, v151
	v_lshl_add_u64 v[34:35], v[4:5], 0, v[6:7]
	s_movk_i32 s2, 0x1000
	v_add_co_u32_e32 v4, vcc, s2, v34
	s_movk_i32 s2, 0x2000
	s_nop 0
	v_addc_co_u32_e32 v5, vcc, 0, v35, vcc
	v_add_co_u32_e32 v8, vcc, s2, v34
	v_lshlrev_b32_e32 v2, 11, v32
	s_nop 0
	v_addc_co_u32_e32 v9, vcc, 0, v35, vcc
	s_movk_i32 s2, 0x3000
	v_mov_b32_e32 v0, s82
	v_mov_b32_e32 v1, s83
	v_ashrrev_i32_e32 v3, 31, v2
	v_add_co_u32_e32 v24, vcc, s2, v34
	s_movk_i32 s2, 0x4000
	s_nop 0
	v_addc_co_u32_e32 v25, vcc, 0, v35, vcc
	v_lshl_add_u64 v[0:1], v[2:3], 2, v[0:1]
	v_lshlrev_b32_e32 v6, 7, v48
	v_add_co_u32_e32 v26, vcc, s2, v34
	v_lshl_add_u64 v[36:37], v[0:1], 0, v[6:7]
	s_nop 0
	v_addc_co_u32_e32 v27, vcc, 0, v35, vcc
	global_load_dword v49, v[34:35], off
	s_waitcnt lgkmcnt(0)
	global_load_dword v50, v[34:35], off offset:1024
	global_load_dword v51, v[34:35], off offset:2048
	global_load_dword v52, v[34:35], off offset:3072
	global_load_dword v53, v[4:5], off offset:1024
	global_load_dword v54, v[4:5], off offset:2048
	global_load_dword v55, v[4:5], off offset:3072
	global_load_dword v56, v[24:25], off offset:1024
	global_load_dword v57, v[8:9], off offset:-4096
	global_load_dword v58, v[8:9], off
	global_load_dword v59, v[8:9], off offset:1024
	global_load_dword v60, v[8:9], off offset:2048
	global_load_dword v61, v[8:9], off offset:3072
	global_load_dword v62, v[26:27], off offset:-4096
	global_load_dword v63, v[26:27], off
	global_load_dword v64, v[26:27], off offset:1024
	global_load_dwordx4 v[0:3], v[36:37], off offset:16
	global_load_dwordx4 v[4:7], v[36:37], off
	global_load_dwordx4 v[8:11], v[36:37], off offset:48
	global_load_dwordx4 v[12:15], v[36:37], off offset:32
	s_movk_i32 s2, 0x5000
	v_add_co_u32_e32 v28, vcc, s2, v34
	s_movk_i32 s2, 0x6000
	s_nop 0
	v_addc_co_u32_e32 v29, vcc, 0, v35, vcc
	v_add_co_u32_e32 v30, vcc, s2, v34
	s_movk_i32 s2, 0x7000
	s_nop 0
	v_addc_co_u32_e32 v31, vcc, 0, v35, vcc
	global_load_dword v65, v[24:25], off offset:2048
	global_load_dword v66, v[24:25], off offset:3072
	global_load_dword v39, v[28:29], off offset:1024
	global_load_dword v40, v[28:29], off offset:2048
	global_load_dword v41, v[28:29], off offset:3072
	global_load_dwordx4 v[16:19], v[36:37], off offset:64
	global_load_dwordx4 v[20:23], v[36:37], off offset:80
	global_load_dword v67, v[26:27], off offset:2048
	global_load_dword v68, v[26:27], off offset:3072
	global_load_dword v38, v[30:31], off offset:-4096
	global_load_dword v42, v[30:31], off
	global_load_dword v43, v[30:31], off offset:1024
	global_load_dword v44, v[30:31], off offset:2048
	global_load_dword v45, v[30:31], off offset:3072
	global_load_dwordx4 v[24:27], v[36:37], off offset:112
	s_nop 0
	global_load_dwordx4 v[28:31], v[36:37], off offset:96
	v_add_co_u32_e32 v34, vcc, s2, v34
	v_readlane_b32 s8, v254, 4
	s_nop 0
	v_addc_co_u32_e32 v35, vcc, 0, v35, vcc
	global_load_dword v36, v[34:35], off
	global_load_dword v37, v[34:35], off offset:1024
	global_load_dword v46, v[34:35], off offset:2048
	global_load_dword v47, v[34:35], off offset:3072
	v_readlane_b32 s10, v254, 6
	v_readlane_b32 s11, v254, 7
	v_readlane_b32 s9, v254, 5
	s_waitcnt vmcnt(22)
	v_fma_f32 v4, v49, v4, 0
	v_fmac_f32_e32 v4, v50, v5
	v_fmac_f32_e32 v4, v51, v6
	v_fmac_f32_e32 v4, v52, v7
	v_fmac_f32_e32 v4, v57, v0
	v_fmac_f32_e32 v4, v53, v1
	v_fmac_f32_e32 v4, v54, v2
	v_fmac_f32_e32 v4, v55, v3
	s_waitcnt vmcnt(20)
	v_fmac_f32_e32 v4, v58, v12
	v_fmac_f32_e32 v4, v59, v13
	v_fmac_f32_e32 v4, v60, v14
	v_fmac_f32_e32 v4, v61, v15
	v_fmac_f32_e32 v4, v62, v8
	v_fmac_f32_e32 v4, v56, v9
	s_waitcnt vmcnt(19)
	v_fmac_f32_e32 v4, v65, v10
	s_waitcnt vmcnt(18)
	v_fmac_f32_e32 v4, v66, v11
	s_waitcnt vmcnt(14)
	v_fmac_f32_e32 v4, v63, v16
	v_fmac_f32_e32 v4, v64, v17
	s_waitcnt vmcnt(12)
	v_fmac_f32_e32 v4, v67, v18
	s_waitcnt vmcnt(11)
	v_fmac_f32_e32 v4, v68, v19
	s_waitcnt vmcnt(10)
	v_pk_mul_f32 v[0:1], v[38:39], v[20:21]
	s_nop 0
	v_add_f32_e32 v0, v4, v0
	v_add_f32_e32 v2, v0, v1
	v_pk_mul_f32 v[0:1], v[40:41], v[22:23]
	s_nop 0
	v_add_f32_e32 v0, v2, v0
	v_add_f32_e32 v2, v0, v1
	s_waitcnt vmcnt(4)
	v_pk_mul_f32 v[0:1], v[42:43], v[28:29]
	s_nop 0
	v_add_f32_e32 v0, v2, v0
	v_add_f32_e32 v2, v0, v1
	v_pk_mul_f32 v[0:1], v[44:45], v[30:31]
	s_nop 0
	v_add_f32_e32 v0, v2, v0
	v_add_f32_e32 v2, v0, v1
	s_waitcnt vmcnt(2)
	v_pk_mul_f32 v[0:1], v[36:37], v[24:25]
	s_nop 0
	v_add_f32_e32 v0, v2, v0
	v_add_f32_e32 v2, v0, v1
	s_waitcnt vmcnt(0)
	v_pk_mul_f32 v[0:1], v[46:47], v[26:27]
	s_nop 0
	v_add_f32_e32 v0, v2, v0
	v_add_f32_e32 v2, v0, v1
	v_lshlrev_b32_e32 v0, 8, v32
	v_lshl_add_u32 v0, v48, 9, v0
	v_or3_b32 v0, v0, v33, v151
	v_ashrrev_i32_e32 v1, 31, v0
	v_lshl_add_u64 v[0:1], v[0:1], 2, s[10:11]
	v_add_co_u32_e32 v0, vcc, 0x1a90000, v0
	s_nop 1
	v_addc_co_u32_e32 v1, vcc, 0, v1, vcc
	global_store_dword v[0:1], v2, off sc1
